# v50: v44 + grid barrier B4 (P3->P3b) replaced by a scan-done counter: P3b only reads GDN scan outputs, so each workgroup starts P3b right after its last P3 item
# speedup vs baseline: 1.0114x; 1.0089x over previous
; __global__ void __launch_bounds__(512, 2) fwd_mega(Params P) {
;     ...
;         if (pr >= 64 + 512) break;
;         if (pr < 64) gdn_scan(P, pr * 2 + team, smem, tt);
;         else { const int fj = pr - 64; fox_attn(P, (fj & 31) * 2 + team, 15 - (fj >> 5), smem, tt); }
;     }
;     }
;     xcd_barrier(xbar, wid_s);
.Lscan_done:
	s_waitcnt vmcnt(0)
	s_barrier
	s_cmp_lg_u32 s84, 0
	s_cbranch_scc1 .LBB0_530
	buffer_wbl2 sc1
	s_waitcnt vmcnt(0)
	s_add_u32 s66, s80, 0x1d83c00
	s_addc_u32 s67, s81, 0
	s_mov_b64 s[64:65], exec
	s_mov_b64 exec, 1
	v_mov_b32_e32 v190, 0
	v_mov_b32_e32 v191, 1
	global_atomic_add v190, v191, s[66:67]
	s_mov_b64 exec, s[64:65]
	s_branch .LBB0_530
.LBB0_591:
	s_or_b64 exec, exec, s[12:13]
	s_waitcnt vmcnt(0)
	v_readlane_b32 s0, v255, 29
	s_barrier
	v_mbcnt_lo_u32_b32 v0, -1, 0
	v_mbcnt_hi_u32_b32 v0, -1, v0
	s_nop 0
	v_cmp_eq_u32_e32 vcc, s0, v0
	s_and_saveexec_b64 s[0:1], vcc
	s_cbranch_execz .LBB0_643
	s_add_u32 s2, s80, 0x1d83c00
	s_addc_u32 s3, s81, 0
	v_mov_b32_e32 v2, 0
	s_mov_b32 s4, 0
.Lp3b_spin:
	global_load_dword v3, v2, s[2:3] sc1
	s_waitcnt vmcnt(0)
	v_readfirstlane_b32 s5, v3
	s_add_i32 s4, s4, 1
	s_cmp_ge_u32 s5, 64
	s_cbranch_scc1 .Lp3b_go
	s_sleep 1
	s_cmp_lt_u32 s4, 0x400
	s_cbranch_scc1 .Lp3b_spin
.Lp3b_go:
	buffer_inv sc1
	s_waitcnt vmcnt(0)
